# v54 + attention store tail no longer waits for the just-issued ticket atomic (vmcnt(1) in the ticket wave), loop-top ticket consume waits vmcnt(4) instead of draining the 4 output stores
# baseline (speedup 1.0000x reference)
; DI unsigned pk2(float a, float b) { f32x2 v = {a, b}; bf2_t r = __builtin_convertvector(v, bf2_t); return __builtin_bit_cast(unsigned, r); }
; DI void attn_unit(const Params& p, int l, int b, int qtp, int grp, char* smem) {
;     ...
;   const int gcol = (grp == 2 ? 0 : grp == 1 ? 256 : grp == 0 ? 512 : 768) + w * 64 + 4 * h;
;   bf16_t* mrow = (bf16_t*)(p.ws + OFF_MIX) + (tok0 + qpos) * DM + gcol;
; #pragma unroll
;   for (int g = 0; g < 4; ++g) {
;     u32x2 a = {pk2(o0[4 * g], o0[4 * g + 1]), pk2(o0[4 * g + 2], o0[4 * g + 3])};
;     u32x2 c = {pk2(o1[4 * g], o1[4 * g + 1]), pk2(o1[4 * g + 2], o1[4 * g + 3])};
;     *(u32x2*)(mrow + 8 * g) = a;
;     *(u32x2*)(mrow + 32 + 8 * g) = c;
;   }
.Lpf_twj:
	v_lshl_add_u64 v[34:35], s[0:1], 0, v[34:35]
	v_lshl_add_u64 v[34:35], v[0:1], 1, v[34:35]
	v_cvt_pk_bf16_f32 v36, v18, v19
	v_cvt_pk_bf16_f32 v37, v20, v21
	v_cvt_pk_bf16_f32 v38, v22, v23
	v_cvt_pk_bf16_f32 v39, v24, v25
	v_cvt_pk_bf16_f32 v40, v26, v27
	v_cvt_pk_bf16_f32 v41, v28, v29
	v_cvt_pk_bf16_f32 v42, v30, v31
	v_cvt_pk_bf16_f32 v43, v32, v33
	v_cvt_pk_bf16_f32 v44, v2, v3
	v_cvt_pk_bf16_f32 v45, v4, v5
	v_cvt_pk_bf16_f32 v46, v6, v7
	v_cvt_pk_bf16_f32 v47, v8, v9
	v_cvt_pk_bf16_f32 v48, v10, v11
	v_cvt_pk_bf16_f32 v49, v12, v13
	v_cvt_pk_bf16_f32 v50, v14, v15
	v_cvt_pk_bf16_f32 v51, v16, v17
	v_and_b32_e32 v52, 32, v203
	v_lshrrev_b32_e32 v52, 2, v52
	v_mov_b32_e32 v53, 0
	v_lshl_add_u64 v[34:35], v[34:35], 0, v[52:53]
	v_permlane32_swap_b32_e32 v36, v38
	v_permlane32_swap_b32_e32 v37, v39
	v_permlane32_swap_b32_e32 v40, v42
	v_permlane32_swap_b32_e32 v41, v43
	v_permlane32_swap_b32_e32 v44, v46
	v_permlane32_swap_b32_e32 v45, v47
	v_permlane32_swap_b32_e32 v48, v50
	v_permlane32_swap_b32_e32 v49, v51
	global_store_dwordx4 v[34:35], v[36:39], off
	global_store_dwordx4 v[34:35], v[40:43], off offset:32
	global_store_dwordx4 v[34:35], v[44:47], off offset:64
	global_store_dwordx4 v[34:35], v[48:51], off offset:96
	s_nop 0

; DI int my_tid() { int t = threadIdx.x; asm volatile("" : "+v"(t)); return t; }
; DI void phase_attn(const Params& p, int l, char* smem) {
;     ...
;     if (my_tid() == 0) {
;       int U = -1;
;       for (; k < 8; ++k) {
;         const int x = (xcd + k) & 7;
;         const int v = atomicAdd(ctr + x, 1);
;         if (v < 512) { U = x * 512 + v; break; }
;       }
;       *su = U;
;     }
.LBB0_115:
	v_mov_b32_e32 v0, v215
	s_waitcnt lgkmcnt(0)
	v_add_u32_e32 v2, s68, v0
	v_and_b32_e32 v2, 7, v2
	v_readlane_b32 s12, v245, 58
	v_lshlrev_b32_e32 v3, 2, v2
	v_readlane_b32 s13, v245, 59
	s_or_b64 s[8:9], s[8:9], exec
	s_or_b64 s[10:11], s[10:11], exec
	s_nop 2
	s_cmp_eq_u32 s99, 0
	s_cbranch_scc0 .Lpf_use
	global_atomic_add v3, v3, v200, s[12:13] sc0
	s_waitcnt vmcnt(0)
	s_branch .Lpf_join
.Lpf_use:
	s_waitcnt vmcnt(4)
	v_mov_b32_e32 v3, v55
	s_mov_b32 s99, 0
.Lpf_join:
	s_movk_i32 s12, 0x1ff
	s_nop 0
	v_cmp_lt_i32_e32 vcc, s12, v3
	s_and_saveexec_b64 s[12:13], vcc
	s_cbranch_execz .LBB0_114
	v_cmp_lt_i32_e32 vcc, 6, v0
	s_andn2_b64 s[10:11], s[10:11], exec
	s_and_b64 s[14:15], vcc, exec
	v_add_u32_e32 v215, 1, v0
	s_andn2_b64 s[8:9], s[8:9], exec
	s_or_b64 s[10:11], s[10:11], s[14:15]
	s_branch .LBB0_114
